# GEMM prologue de-serialisation: second fill batch of LDS-DMA loads issued before the first wait (all 7 GEMM phases)
# baseline (speedup 1.0000x reference)
; __device__ __forceinline__ int fresh_tid() { int t = (int)threadIdx.x; asm volatile("" : "+v"(t)); return t; }
; #define PG8_STAGE(bufoff, gbase, voff) do { _Pragma("unroll") for (int _i = 0; _i < 2; ++_i) \
;         __builtin_amdgcn_global_load_lds((const unsigned*)((const char*)(gbase) + (voff)[_i]), (PG8_LAS unsigned*)(lds + (bufoff) + ldsw + _i * 8192), 16, 0, 0); } while (0)
; #define PG8_WAIT_V(n) asm volatile("s_waitcnt vmcnt(" #n ")" ::: "memory")
; #define PG8_BAR __builtin_amdgcn_s_barrier()
; template <class Epi, class Sched, bool ALIGN_EPI = false, bool SP2 = false>
; __device__ __forceinline__ void gemm_phase(PG8_LAS unsigned char* lds, const Gemm g, const Sched& S, const Epi& E) {
;     const int tid = fresh_tid(), wid = __builtin_amdgcn_readfirstlane(tid >> 6), lane = tid & 63, wr = wid >> 2, wc = wid & 3, fr = lane & 15, fq = lane >> 4;
;     const int K = g.K, nt = K / BK;
;     unsigned voffA[2], voffB[2];
; #pragma unroll
;     for (int i = 0; i < 2; ++i) { int R, C; stage_rc(tid * 16 + i * 8192, R, C); const int Rb = Epi::PERM ? ((R & ~31) + perm32(R & 31)) : R;
;         voffA[i] = (unsigned)(R * K + C) * 2u; voffB[i] = (unsigned)(Rb * K + C) * 2u; }
;     const size_t kstep = (size_t)(BK * 2);
;     const size_t hstep = (size_t)HALF * K * 2;
;     const size_t tstep = 2 * hstep;
;     const unsigned ldsw = (unsigned)wid * 1024u;
;     const int aoff = lds_byte(wr * 64 + fr, fq * 8), boff = lds_byte(wc * 32 + fr, fq * 8);
;     ...
;     if constexpr (SP2) {
;         PG8_STAGE(PG8_SB(0, 0), cB, voffB); PG8_STAGE(PG8_SB(0, 1), cB + hstep, voffB); PG8_STAGE(PG8_SA(0, 0), cA, voffA); PG8_STAGE(PG8_SA(0, 1), cA + hstep, voffA);
;         if (wr == 1) PG8_BAR;
;         PG8_WAIT_V(2); PG8_BAR;
;         PG8_STAGE(PG8_SB(1, 0), cB + kstep, voffB); PG8_STAGE(PG8_SA(1, 0), cA + kstep, voffA); PG8_STAGE(PG8_SB(1, 1), cB + hstep + kstep, voffB);
;         PG8_WAIT_V(6); PG8_BAR;
.LBB0_206:
	s_waitcnt lgkmcnt(0)
	s_add_u32 s12, s4, 0xb200000
	s_addc_u32 s13, s5, 0
	s_lshl_b32 s0, s14, 5
	s_mov_b64 s[14:15], 0x80
	s_and_b32 s3, s0, 0x60
	s_add_i32 m0, s27, 0x18000
	v_lshl_add_u64 v[6:7], v[6:7], 0, s[14:15]
	s_lshl_b32 s2, s11, 13
	s_lshl_b32 s4, s3, 7
	s_nop 0
	global_load_lds_dwordx4 v[6:7], off
	v_lshl_add_u64 v[4:5], v[4:5], 0, s[14:15]
	s_add_i32 m0, s27, 0x1a000
	s_add_i32 s52, s27, 0x8000
	s_add_i32 s53, s27, 0xa000
	global_load_lds_dwordx4 v[4:5], off
	v_lshl_add_u64 v[0:1], v[0:1], 0, s[14:15]
	s_mov_b32 m0, s52
	s_add_u32 s0, s30, 0x40080
	global_load_lds_dwordx4 v[0:1], off
	v_lshl_add_u64 v[0:1], v[2:3], 0, s[14:15]
	s_mov_b32 m0, s53
	s_addc_u32 s1, s31, 0
	global_load_lds_dwordx4 v[0:1], off
	s_add_i32 m0, s27, 0x1c000
	v_lshl_add_u64 v[0:1], s[0:1], 0, v[132:133]
	global_load_lds_dwordx4 v[0:1], off
	v_lshl_add_u64 v[0:1], s[0:1], 0, v[128:129]
	s_add_i32 m0, s27, 0x1e000
	s_cmpk_lt_u32 s10, 0x100
	global_load_lds_dwordx4 v[0:1], off
	s_waitcnt vmcnt(8)
	s_barrier
	v_lshrrev_b32_e32 v1, 1, v8
	v_and_b32_e32 v1, 24, v1
	v_and_b32_e32 v0, 15, v8
	v_lshlrev_b32_e32 v2, 1, v1
	v_lshl_or_b32 v148, s11, 6, v0
	v_lshl_or_b32 v0, v0, 6, v2
	v_lshlrev_b32_e32 v2, 2, v8
	v_and_b32_e32 v2, 32, v2
	v_bitop3_b32 v3, v0, s2, v2 bitop3:0xde
	v_bitop3_b32 v149, v0, s4, v2 bitop3:0xde
	v_and_b32_e32 v239, 15, v8
	v_and_b32_e32 v240, 7, v239
	v_lshrrev_b32_e32 v239, 3, v239
	v_lshlrev_b32_e32 v239, 10, v239
	v_lshl_add_u32 v239, v240, 7, v239
	v_bfe_u32 v241, v8, 4, 2
	v_xor_b32_e32 v242, v241, v240
	v_or_b32_e32 v241, 4, v241
	v_xor_b32_e32 v243, v241, v240
	v_lshl_add_u32 v242, v242, 4, v239
	v_lshl_add_u32 v243, v243, 4, v239
	v_lshrrev_b32_e32 v244, 8, v8
	v_lshlrev_b32_e32 v244, 13, v244
	v_add_u32_e32 v3, v244, v242
	v_add_u32_e32 v233, v244, v243
	v_bfe_u32 v244, v8, 6, 2
	v_lshlrev_b32_e32 v244, 12, v244
	v_add_u32_e32 v149, v244, v242
	v_add_u32_e32 v234, v244, v243
	v_lshlrev_b32_e32 v0, 14, v13
	v_and_b32_e32 v0, 0xffff8000, v0
	v_or_b32_e32 v150, s3, v1
	v_lshl_add_u32 v0, v12, 11, v0
	v_and_b32_e32 v1, 1, v13
	v_lshl_or_b32 v0, v1, 6, v0
	v_lshl_add_u32 v136, v14, 1, v0
	v_mov_b32_e32 v136, v134
	v_lshlrev_b32_e32 v0, 14, v9
	v_and_b32_e32 v0, 0xffff8000, v0
	s_waitcnt vmcnt(6)
	v_lshl_add_u32 v0, v10, 11, v0
	v_and_b32_e32 v1, 1, v9
	s_sext_i32_i16 s59, s16
	s_cselect_b64 s[16:17], -1, 0
	v_lshl_or_b32 v0, v1, 6, v0
	s_add_i32 s56, 0, 0x10000
	s_add_i32 s57, 0, 0x14000
	s_ashr_i32 s54, s94, 31
	s_mov_b32 s55, s94
	v_mov_b32_e32 v137, v133
	v_lshl_add_u32 v138, v11, 1, v0
	v_mov_b32_e32 v138, v130
	v_mov_b32_e32 v139, v133
	v_mov_b64_e32 v[140:141], 0xb00
	v_mov_b64_e32 v[142:143], 0xaff
	v_add_u32_e32 v151, s56, v149
	v_add_u32_e32 v235, s56, v234
	v_add_u32_e32 v152, s57, v149
	v_add_u32_e32 v236, s57, v234
	v_add_u32_e32 v153, 0, v3
	s_movk_i32 s58, 0x1600
	s_barrier
	s_branch .LBB0_209

; __device__ __forceinline__ int fresh_tid() { int t = (int)threadIdx.x; asm volatile("" : "+v"(t)); return t; }
; #define PG8_STAGE(bufoff, gbase, voff) do { _Pragma("unroll") for (int _i = 0; _i < 2; ++_i) \
;         __builtin_amdgcn_global_load_lds((const unsigned*)((const char*)(gbase) + (voff)[_i]), (PG8_LAS unsigned*)(lds + (bufoff) + ldsw + _i * 8192), 16, 0, 0); } while (0)
; #define PG8_WAIT_V(n) asm volatile("s_waitcnt vmcnt(" #n ")" ::: "memory")
; #define PG8_BAR __builtin_amdgcn_s_barrier()
; template <class Epi, class Sched, bool ALIGN_EPI = false, bool SP2 = false>
; __device__ __forceinline__ void gemm_phase(PG8_LAS unsigned char* lds, const Gemm g, const Sched& S, const Epi& E) {
;     const int tid = fresh_tid(), wid = __builtin_amdgcn_readfirstlane(tid >> 6), lane = tid & 63, wr = wid >> 2, wc = wid & 3, fr = lane & 15, fq = lane >> 4;
;     const int K = g.K, nt = K / BK;
;     unsigned voffA[2], voffB[2];
; #pragma unroll
;     for (int i = 0; i < 2; ++i) { int R, C; stage_rc(tid * 16 + i * 8192, R, C); const int Rb = Epi::PERM ? ((R & ~31) + perm32(R & 31)) : R;
;         voffA[i] = (unsigned)(R * K + C) * 2u; voffB[i] = (unsigned)(Rb * K + C) * 2u; }
;     const size_t kstep = (size_t)(BK * 2);
;     const size_t hstep = (size_t)HALF * K * 2;
;     const size_t tstep = 2 * hstep;
;     const unsigned ldsw = (unsigned)wid * 1024u;
;     const int aoff = lds_byte(wr * 64 + fr, fq * 8), boff = lds_byte(wc * 32 + fr, fq * 8);
;     ...
;     if constexpr (SP2) {
;         PG8_STAGE(PG8_SB(0, 0), cB, voffB); PG8_STAGE(PG8_SB(0, 1), cB + hstep, voffB); PG8_STAGE(PG8_SA(0, 0), cA, voffA); PG8_STAGE(PG8_SA(0, 1), cA + hstep, voffA);
;         if (wr == 1) PG8_BAR;
;         PG8_WAIT_V(2); PG8_BAR;
;         PG8_STAGE(PG8_SB(1, 0), cB + kstep, voffB); PG8_STAGE(PG8_SA(1, 0), cA + kstep, voffA); PG8_STAGE(PG8_SB(1, 1), cB + hstep + kstep, voffB);
;         PG8_WAIT_V(6); PG8_BAR;
.LBB0_289:
	s_add_u32 s14, s6, 0x7100000
	s_addc_u32 s15, s7, 0
	s_lshl_b32 s1, s9, 5
	s_mov_b64 s[16:17], 0x80
	s_and_b32 s9, s1, 0x60
	s_add_i32 m0, s53, 0x18000
	v_lshl_add_u64 v[6:7], v[6:7], 0, s[16:17]
	s_lshl_b32 s3, s11, 13
	s_lshl_b32 s19, s9, 7
	s_nop 0
	global_load_lds_dwordx4 v[6:7], off
	v_lshl_add_u64 v[4:5], v[4:5], 0, s[16:17]
	s_add_i32 m0, s53, 0x1a000
	s_add_i32 s58, s53, 0x8000
	s_add_i32 s59, s53, 0xa000
	global_load_lds_dwordx4 v[4:5], off
	v_lshl_add_u64 v[0:1], v[0:1], 0, s[16:17]
	s_mov_b32 m0, s58
	s_add_u32 s6, s34, 0xb0080
	global_load_lds_dwordx4 v[0:1], off
	v_lshl_add_u64 v[0:1], v[2:3], 0, s[16:17]
	s_mov_b32 m0, s59
	s_addc_u32 s7, s35, 0
	global_load_lds_dwordx4 v[0:1], off
	s_add_i32 m0, s53, 0x1c000
	v_lshl_add_u64 v[0:1], s[6:7], 0, v[130:131]
	global_load_lds_dwordx4 v[0:1], off
	v_lshl_add_u64 v[0:1], s[6:7], 0, v[134:135]
	s_add_i32 m0, s53, 0x1e000
	s_cmpk_lt_u32 s10, 0x100
	global_load_lds_dwordx4 v[0:1], off
	s_waitcnt vmcnt(8)
	s_barrier
	v_lshrrev_b32_e32 v1, 1, v8
	v_and_b32_e32 v1, 24, v1
	v_and_b32_e32 v0, 15, v8
	v_lshlrev_b32_e32 v2, 1, v1
	v_lshl_or_b32 v144, s11, 6, v0
	v_lshl_or_b32 v0, v0, 6, v2
	v_lshlrev_b32_e32 v2, 2, v8
	v_and_b32_e32 v2, 32, v2
	v_bitop3_b32 v3, v0, s3, v2 bitop3:0xde
	v_bitop3_b32 v145, v0, s19, v2 bitop3:0xde
	v_and_b32_e32 v239, 15, v8
	v_and_b32_e32 v240, 7, v239
	v_lshrrev_b32_e32 v239, 3, v239
	v_lshlrev_b32_e32 v239, 10, v239
	v_lshl_add_u32 v239, v240, 7, v239
	v_bfe_u32 v241, v8, 4, 2
	v_xor_b32_e32 v242, v241, v240
	v_or_b32_e32 v241, 4, v241
	v_xor_b32_e32 v243, v241, v240
	v_lshl_add_u32 v242, v242, 4, v239
	v_lshl_add_u32 v243, v243, 4, v239
	v_lshrrev_b32_e32 v244, 8, v8
	v_lshlrev_b32_e32 v244, 13, v244
	v_add_u32_e32 v3, v244, v242
	v_add_u32_e32 v233, v244, v243
	v_bfe_u32 v244, v8, 6, 2
	v_lshlrev_b32_e32 v244, 12, v244
	v_add_u32_e32 v145, v244, v242
	v_add_u32_e32 v234, v244, v243
	v_or_b32_e32 v146, s9, v1
	v_lshrrev_b32_e32 v1, 1, v9
	v_mul_lo_u32 v0, v11, s8
	s_mov_b32 s3, 0xb000
	v_mad_u64_u32 v[0:1], s[10:11], v1, s3, v[0:1]
	v_or_b32_e32 v0, v0, v10
	s_mov_b64 s[6:7], 0xb0080
	v_add_lshl_u32 v0, v0, v12, 1
	v_mov_b32_e32 v1, v131
	v_lshl_add_u64 v[136:137], v[0:1], 0, s[6:7]
	v_add_u32_e32 v136, 0xb0080, v128
	v_mov_b32_e32 v137, 0
	v_lshrrev_b32_e32 v1, 1, v13
	v_mul_lo_u32 v0, v14, s8
	v_mad_u64_u32 v[0:1], s[8:9], v1, s3, v[0:1]
	s_waitcnt vmcnt(6)
	v_or_b32_e32 v0, v0, v15
	s_sext_i32_i8 s1, s18
	s_cselect_b64 s[18:19], -1, 0
	v_add_lshl_u32 v0, v0, v16, 1
	v_mov_b32_e32 v1, v131
	s_add_i32 s62, 0, 0x10000
	s_add_i32 s63, 0, 0x14000
	s_ashr_i32 s60, s94, 31
	s_mov_b32 s61, s94
	v_lshl_add_u64 v[138:139], v[0:1], 0, s[6:7]
	v_add_u32_e32 v138, 0xb0080, v132
	v_mov_b32_e32 v139, 0
	v_mov_b64_e32 v[140:141], 0x200
	v_mov_b64_e32 v[142:143], 0x1ff
	v_add_u32_e32 v147, s62, v145
	v_add_u32_e32 v235, s62, v234
	v_add_u32_e32 v148, s63, v145
	v_add_u32_e32 v236, s63, v234
	v_add_u32_e32 v149, 0, v3
	s_mov_b64 s[20:21], 0x40000
	s_mov_b32 s64, 0x40000
	s_mov_b64 s[22:23], 0x48000
	s_mov_b32 s65, 0x48000
	s_mov_b64 s[24:25], 0x50000
	s_mov_b32 s66, 0x50000
	s_mov_b64 s[26:27], 0x58000
	s_mov_b32 s67, 0x58000
	s_barrier
	s_branch .LBB0_292

; __device__ __forceinline__ int fresh_tid() { int t = (int)threadIdx.x; asm volatile("" : "+v"(t)); return t; }
; #define PG8_STAGE(bufoff, gbase, voff) do { _Pragma("unroll") for (int _i = 0; _i < 2; ++_i) \
;         __builtin_amdgcn_global_load_lds((const unsigned*)((const char*)(gbase) + (voff)[_i]), (PG8_LAS unsigned*)(lds + (bufoff) + ldsw + _i * 8192), 16, 0, 0); } while (0)
; #define PG8_WAIT_V(n) asm volatile("s_waitcnt vmcnt(" #n ")" ::: "memory")
; #define PG8_BAR __builtin_amdgcn_s_barrier()
; template <class Epi, class Sched, bool ALIGN_EPI = false, bool SP2 = false>
; __device__ __forceinline__ void gemm_phase(PG8_LAS unsigned char* lds, const Gemm g, const Sched& S, const Epi& E) {
;     const int tid = fresh_tid(), wid = __builtin_amdgcn_readfirstlane(tid >> 6), lane = tid & 63, wr = wid >> 2, wc = wid & 3, fr = lane & 15, fq = lane >> 4;
;     const int K = g.K, nt = K / BK;
;     unsigned voffA[2], voffB[2];
; #pragma unroll
;     for (int i = 0; i < 2; ++i) { int R, C; stage_rc(tid * 16 + i * 8192, R, C); const int Rb = Epi::PERM ? ((R & ~31) + perm32(R & 31)) : R;
;         voffA[i] = (unsigned)(R * K + C) * 2u; voffB[i] = (unsigned)(Rb * K + C) * 2u; }
;     const size_t kstep = (size_t)(BK * 2);
;     const size_t hstep = (size_t)HALF * K * 2;
;     const size_t tstep = 2 * hstep;
;     const unsigned ldsw = (unsigned)wid * 1024u;
;     const int aoff = lds_byte(wr * 64 + fr, fq * 8), boff = lds_byte(wc * 32 + fr, fq * 8);
;     ...
;     if constexpr (SP2) {
;         PG8_STAGE(PG8_SB(0, 0), cB, voffB); PG8_STAGE(PG8_SB(0, 1), cB + hstep, voffB); PG8_STAGE(PG8_SA(0, 0), cA, voffA); PG8_STAGE(PG8_SA(0, 1), cA + hstep, voffA);
;         if (wr == 1) PG8_BAR;
;         PG8_WAIT_V(2); PG8_BAR;
;         PG8_STAGE(PG8_SB(1, 0), cB + kstep, voffB); PG8_STAGE(PG8_SA(1, 0), cA + kstep, voffA); PG8_STAGE(PG8_SB(1, 1), cB + hstep + kstep, voffB);
;         PG8_WAIT_V(6); PG8_BAR;
.LBB0_488:
	s_waitcnt lgkmcnt(0)
	s_add_u32 s12, s8, 0xb200000
	s_addc_u32 s13, s9, 0
	s_lshl_b32 s0, s14, 5
	s_mov_b64 s[14:15], 0x80
	s_and_b32 s8, s0, 0x60
	s_add_i32 m0, s43, 0x18000
	v_lshl_add_u64 v[6:7], v[6:7], 0, s[14:15]
	s_lshl_b32 s3, s17, 13
	s_lshl_b32 s9, s8, 7
	s_nop 0
	global_load_lds_dwordx4 v[6:7], off
	v_lshl_add_u64 v[4:5], v[4:5], 0, s[14:15]
	s_add_i32 m0, s43, 0x1a000
	s_add_i32 s56, s43, 0x8000
	s_add_i32 s57, s43, 0xa000
	global_load_lds_dwordx4 v[4:5], off
	v_lshl_add_u64 v[0:1], v[0:1], 0, s[14:15]
	s_mov_b32 m0, s56
	s_add_u32 s0, s34, 0x40080
	global_load_lds_dwordx4 v[0:1], off
	v_lshl_add_u64 v[0:1], v[2:3], 0, s[14:15]
	s_mov_b32 m0, s57
	s_addc_u32 s1, s35, 0
	global_load_lds_dwordx4 v[0:1], off
	s_add_i32 m0, s43, 0x1c000
	v_lshl_add_u64 v[0:1], s[0:1], 0, v[130:131]
	global_load_lds_dwordx4 v[0:1], off
	v_lshl_add_u64 v[0:1], s[0:1], 0, v[134:135]
	s_add_i32 m0, s43, 0x1e000
	s_cmpk_lt_u32 s16, 0x100
	global_load_lds_dwordx4 v[0:1], off
	s_waitcnt vmcnt(8)
	s_barrier
	v_lshrrev_b32_e32 v1, 1, v8
	v_and_b32_e32 v1, 24, v1
	v_and_b32_e32 v0, 15, v8
	v_lshlrev_b32_e32 v2, 1, v1
	v_lshl_or_b32 v146, s17, 6, v0
	v_lshl_or_b32 v0, v0, 6, v2
	v_lshlrev_b32_e32 v2, 2, v8
	v_and_b32_e32 v2, 32, v2
	v_bitop3_b32 v3, v0, s3, v2 bitop3:0xde
	v_bitop3_b32 v147, v0, s9, v2 bitop3:0xde
	v_and_b32_e32 v239, 15, v8
	v_and_b32_e32 v240, 7, v239
	v_lshrrev_b32_e32 v239, 3, v239
	v_lshlrev_b32_e32 v239, 10, v239
	v_lshl_add_u32 v239, v240, 7, v239
	v_bfe_u32 v241, v8, 4, 2
	v_xor_b32_e32 v242, v241, v240
	v_or_b32_e32 v241, 4, v241
	v_xor_b32_e32 v243, v241, v240
	v_lshl_add_u32 v242, v242, 4, v239
	v_lshl_add_u32 v243, v243, 4, v239
	v_lshrrev_b32_e32 v244, 8, v8
	v_lshlrev_b32_e32 v244, 13, v244
	v_add_u32_e32 v3, v244, v242
	v_add_u32_e32 v233, v244, v243
	v_bfe_u32 v244, v8, 6, 2
	v_lshlrev_b32_e32 v244, 12, v244
	v_add_u32_e32 v147, v244, v242
	v_add_u32_e32 v234, v244, v243
	v_lshlrev_b32_e32 v0, 14, v9
	v_and_b32_e32 v0, 0xffff8000, v0
	v_or_b32_e32 v148, s8, v1
	v_lshl_add_u32 v0, v10, 11, v0
	v_and_b32_e32 v1, 1, v9
	v_lshl_or_b32 v0, v1, 6, v0
	v_lshl_add_u32 v136, v11, 1, v0
	v_mov_b32_e32 v136, v128
	v_lshlrev_b32_e32 v0, 14, v12
	v_and_b32_e32 v0, 0xffff8000, v0
	s_waitcnt vmcnt(6)
	v_lshl_add_u32 v0, v13, 11, v0
	v_and_b32_e32 v1, 1, v12
	s_cselect_b64 s[16:17], -1, 0
	v_lshl_or_b32 v0, v1, 6, v0
	s_add_i32 s62, 0, 0x10000
	s_add_i32 s63, 0, 0x14000
	s_ashr_i32 s58, s94, 31
	s_mov_b32 s59, s94
	s_ashr_i32 s60, s33, 31
	v_mov_b32_e32 v137, v131
	v_lshl_add_u32 v138, v14, 1, v0
	v_mov_b32_e32 v138, v132
	v_mov_b32_e32 v139, v131
	v_mov_b64_e32 v[140:141], 0x300
	v_mov_b64_e32 v[142:143], 0x2ff
	s_movk_i32 s61, 0x61
	v_add_u32_e32 v149, s62, v147
	v_add_u32_e32 v235, s62, v234
	v_add_u32_e32 v150, s63, v147
	v_add_u32_e32 v236, s63, v234
	v_add_u32_e32 v151, 0, v3
	s_movk_i32 s64, 0xc00
	s_barrier
	s_branch .LBB0_491

; __device__ __forceinline__ int fresh_tid() { int t = (int)threadIdx.x; asm volatile("" : "+v"(t)); return t; }
; #define PG8_STAGE(bufoff, gbase, voff) do { _Pragma("unroll") for (int _i = 0; _i < 2; ++_i) \
;         __builtin_amdgcn_global_load_lds((const unsigned*)((const char*)(gbase) + (voff)[_i]), (PG8_LAS unsigned*)(lds + (bufoff) + ldsw + _i * 8192), 16, 0, 0); } while (0)
; #define PG8_WAIT_V(n) asm volatile("s_waitcnt vmcnt(" #n ")" ::: "memory")
; #define PG8_BAR __builtin_amdgcn_s_barrier()
; template <class Epi, class Sched, bool ALIGN_EPI = false, bool SP2 = false>
; __device__ __forceinline__ void gemm_phase(PG8_LAS unsigned char* lds, const Gemm g, const Sched& S, const Epi& E) {
;     const int tid = fresh_tid(), wid = __builtin_amdgcn_readfirstlane(tid >> 6), lane = tid & 63, wr = wid >> 2, wc = wid & 3, fr = lane & 15, fq = lane >> 4;
;     const int K = g.K, nt = K / BK;
;     unsigned voffA[2], voffB[2];
; #pragma unroll
;     for (int i = 0; i < 2; ++i) { int R, C; stage_rc(tid * 16 + i * 8192, R, C); const int Rb = Epi::PERM ? ((R & ~31) + perm32(R & 31)) : R;
;         voffA[i] = (unsigned)(R * K + C) * 2u; voffB[i] = (unsigned)(Rb * K + C) * 2u; }
;     const size_t kstep = (size_t)(BK * 2);
;     const size_t hstep = (size_t)HALF * K * 2;
;     const size_t tstep = 2 * hstep;
;     const unsigned ldsw = (unsigned)wid * 1024u;
;     const int aoff = lds_byte(wr * 64 + fr, fq * 8), boff = lds_byte(wc * 32 + fr, fq * 8);
;     ...
;     if constexpr (SP2) {
;         PG8_STAGE(PG8_SB(0, 0), cB, voffB); PG8_STAGE(PG8_SB(0, 1), cB + hstep, voffB); PG8_STAGE(PG8_SA(0, 0), cA, voffA); PG8_STAGE(PG8_SA(0, 1), cA + hstep, voffA);
;         if (wr == 1) PG8_BAR;
;         PG8_WAIT_V(2); PG8_BAR;
;         PG8_STAGE(PG8_SB(1, 0), cB + kstep, voffB); PG8_STAGE(PG8_SA(1, 0), cA + kstep, voffA); PG8_STAGE(PG8_SB(1, 1), cB + hstep + kstep, voffB);
;         PG8_WAIT_V(6); PG8_BAR;
.LBB0_750:
	s_add_u32 s14, s14, 0x16400400
	s_addc_u32 s15, s15, 0
	s_add_u32 s16, s8, 0x11300000
	s_addc_u32 s17, s9, 0
	s_lshl_b32 s0, s18, 5
	s_mov_b64 s[18:19], 0x80
	s_and_b32 s8, s0, 0x60
	s_add_i32 m0, s31, 0x18000
	v_lshl_add_u64 v[6:7], v[6:7], 0, s[18:19]
	s_lshl_b32 s3, s21, 13
	s_lshl_b32 s9, s8, 7
	s_nop 0
	global_load_lds_dwordx4 v[6:7], off
	v_lshl_add_u64 v[4:5], v[4:5], 0, s[18:19]
	s_add_i32 m0, s31, 0x1a000
	s_add_i32 s57, s31, 0x8000
	s_add_i32 s58, s31, 0xa000
	global_load_lds_dwordx4 v[4:5], off
	v_lshl_add_u64 v[0:1], v[0:1], 0, s[18:19]
	s_mov_b32 m0, s57
	s_add_u32 s0, s36, 0x20080
	global_load_lds_dwordx4 v[0:1], off
	v_lshl_add_u64 v[0:1], v[2:3], 0, s[18:19]
	s_mov_b32 m0, s58
	s_addc_u32 s1, s37, 0
	global_load_lds_dwordx4 v[0:1], off
	s_add_i32 m0, s31, 0x1c000
	v_lshl_add_u64 v[0:1], s[0:1], 0, v[138:139]
	global_load_lds_dwordx4 v[0:1], off
	v_lshl_add_u64 v[0:1], s[0:1], 0, v[142:143]
	s_add_i32 m0, s31, 0x1e000
	s_cmpk_lt_u32 s24, 0x100
	global_load_lds_dwordx4 v[0:1], off
	s_waitcnt vmcnt(8)
	s_barrier
	v_lshrrev_b32_e32 v1, 1, v8
	v_and_b32_e32 v1, 24, v1
	v_and_b32_e32 v0, 15, v8
	v_lshlrev_b32_e32 v2, 1, v1
	v_lshl_or_b32 v164, s21, 6, v0
	v_lshl_or_b32 v0, v0, 6, v2
	v_lshlrev_b32_e32 v2, 2, v8
	v_and_b32_e32 v2, 32, v2
	v_bitop3_b32 v3, v0, s3, v2 bitop3:0xde
	v_bitop3_b32 v165, v0, s9, v2 bitop3:0xde
	v_lshlrev_b32_e32 v0, 13, v9
	v_and_b32_e32 v0, 0xffffc000, v0
	v_or_b32_e32 v166, s8, v1
	v_lshl_add_u32 v0, v10, 10, v0
	v_and_b32_e32 v1, 1, v9
	v_lshl_or_b32 v0, v1, 6, v0
	v_lshl_add_u32 v144, v11, 1, v0
	v_lshlrev_b32_e32 v0, 13, v12
	v_and_b32_e32 v0, 0xffffc000, v0
	s_waitcnt vmcnt(6)
	v_lshl_add_u32 v0, v13, 10, v0
	v_and_b32_e32 v1, 1, v12
	s_sext_i32_i8 s63, s20
	s_cselect_b64 s[20:21], -1, 0
	v_lshl_or_b32 v0, v1, 6, v0
	s_add_i32 s61, 0, 0x10000
	s_add_i32 s62, 0, 0x14000
	s_ashr_i32 s59, s94, 31
	s_mov_b32 s60, s94
	v_mov_b32_e32 v145, v139
	v_lshl_add_u32 v146, v14, 1, v0
	v_mov_b32_e32 v147, v139
	v_mov_b64_e32 v[148:149], 0x100
	v_mov_b64_e32 v[150:151], 0xff
	v_add_u32_e32 v167, s61, v165
	v_add_u32_e32 v168, s62, v165
	v_add_u32_e32 v169, 0, v3
	s_barrier
	s_branch .LBB0_753

; __device__ __forceinline__ int fresh_tid() { int t = (int)threadIdx.x; asm volatile("" : "+v"(t)); return t; }
; #define PG8_STAGE(bufoff, gbase, voff) do { _Pragma("unroll") for (int _i = 0; _i < 2; ++_i) \
;         __builtin_amdgcn_global_load_lds((const unsigned*)((const char*)(gbase) + (voff)[_i]), (PG8_LAS unsigned*)(lds + (bufoff) + ldsw + _i * 8192), 16, 0, 0); } while (0)
; #define PG8_WAIT_V(n) asm volatile("s_waitcnt vmcnt(" #n ")" ::: "memory")
; #define PG8_BAR __builtin_amdgcn_s_barrier()
; template <class Epi, class Sched, bool ALIGN_EPI = false, bool SP2 = false>
; __device__ __forceinline__ void gemm_phase(PG8_LAS unsigned char* lds, const Gemm g, const Sched& S, const Epi& E) {
;     const int tid = fresh_tid(), wid = __builtin_amdgcn_readfirstlane(tid >> 6), lane = tid & 63, wr = wid >> 2, wc = wid & 3, fr = lane & 15, fq = lane >> 4;
;     const int K = g.K, nt = K / BK;
;     unsigned voffA[2], voffB[2];
; #pragma unroll
;     for (int i = 0; i < 2; ++i) { int R, C; stage_rc(tid * 16 + i * 8192, R, C); const int Rb = Epi::PERM ? ((R & ~31) + perm32(R & 31)) : R;
;         voffA[i] = (unsigned)(R * K + C) * 2u; voffB[i] = (unsigned)(Rb * K + C) * 2u; }
;     const size_t kstep = (size_t)(BK * 2);
;     const size_t hstep = (size_t)HALF * K * 2;
;     const size_t tstep = 2 * hstep;
;     const unsigned ldsw = (unsigned)wid * 1024u;
;     const int aoff = lds_byte(wr * 64 + fr, fq * 8), boff = lds_byte(wc * 32 + fr, fq * 8);
;     ...
;     if constexpr (SP2) {
;         PG8_STAGE(PG8_SB(0, 0), cB, voffB); PG8_STAGE(PG8_SB(0, 1), cB + hstep, voffB); PG8_STAGE(PG8_SA(0, 0), cA, voffA); PG8_STAGE(PG8_SA(0, 1), cA + hstep, voffA);
;         if (wr == 1) PG8_BAR;
;         PG8_WAIT_V(2); PG8_BAR;
;         PG8_STAGE(PG8_SB(1, 0), cB + kstep, voffB); PG8_STAGE(PG8_SA(1, 0), cA + kstep, voffA); PG8_STAGE(PG8_SB(1, 1), cB + hstep + kstep, voffB);
;         PG8_WAIT_V(6); PG8_BAR;
.LBB0_919:
	s_add_u32 s16, s10, 0x7100000
	s_addc_u32 s17, s11, 0
	s_lshl_b32 s0, s18, 5
	s_mov_b64 s[18:19], 0x80
	s_and_b32 s10, s0, 0x60
	s_add_i32 m0, s39, 0x18000
	v_lshl_add_u64 v[6:7], v[6:7], 0, s[18:19]
	s_lshl_b32 s3, s22, 13
	s_lshl_b32 s11, s10, 7
	s_nop 0
	global_load_lds_dwordx4 v[6:7], off
	v_lshl_add_u64 v[2:3], v[2:3], 0, s[18:19]
	s_add_i32 m0, s39, 0x1a000
	s_add_i32 s61, s39, 0x8000
	s_add_i32 s62, s39, 0xa000
	global_load_lds_dwordx4 v[2:3], off
	v_lshl_add_u64 v[0:1], v[0:1], 0, s[18:19]
	s_mov_b32 m0, s61
	s_add_u32 s0, s50, 0x40080
	global_load_lds_dwordx4 v[0:1], off
	v_lshl_add_u64 v[0:1], v[4:5], 0, s[18:19]
	s_mov_b32 m0, s62
	s_addc_u32 s1, s51, 0
	global_load_lds_dwordx4 v[0:1], off
	s_add_i32 m0, s39, 0x1c000
	v_lshl_add_u64 v[0:1], s[0:1], 0, v[130:131]
	global_load_lds_dwordx4 v[0:1], off
	v_lshl_add_u64 v[0:1], s[0:1], 0, v[134:135]
	s_add_i32 m0, s39, 0x1e000
	s_cmpk_lt_u32 s21, 0x100
	global_load_lds_dwordx4 v[0:1], off
	s_waitcnt vmcnt(8)
	s_barrier
	v_lshrrev_b32_e32 v1, 1, v8
	v_and_b32_e32 v1, 24, v1
	v_and_b32_e32 v0, 15, v8
	v_lshlrev_b32_e32 v2, 1, v1
	v_lshl_or_b32 v144, s22, 6, v0
	v_lshl_or_b32 v0, v0, 6, v2
	v_lshlrev_b32_e32 v2, 2, v8
	v_and_b32_e32 v2, 32, v2
	v_bitop3_b32 v3, v0, s3, v2 bitop3:0xde
	v_bitop3_b32 v145, v0, s11, v2 bitop3:0xde
	v_and_b32_e32 v239, 15, v8
	v_and_b32_e32 v240, 7, v239
	v_lshrrev_b32_e32 v239, 3, v239
	v_lshlrev_b32_e32 v239, 10, v239
	v_lshl_add_u32 v239, v240, 7, v239
	v_bfe_u32 v241, v8, 4, 2
	v_xor_b32_e32 v242, v241, v240
	v_or_b32_e32 v241, 4, v241
	v_xor_b32_e32 v243, v241, v240
	v_lshl_add_u32 v242, v242, 4, v239
	v_lshl_add_u32 v243, v243, 4, v239
	v_lshrrev_b32_e32 v244, 8, v8
	v_lshlrev_b32_e32 v244, 13, v244
	v_add_u32_e32 v3, v244, v242
	v_add_u32_e32 v233, v244, v243
	v_bfe_u32 v244, v8, 6, 2
	v_lshlrev_b32_e32 v244, 12, v244
	v_add_u32_e32 v145, v244, v242
	v_add_u32_e32 v234, v244, v243
	v_lshlrev_b32_e32 v0, 14, v9
	v_and_b32_e32 v0, 0xffff8000, v0
	v_or_b32_e32 v146, s10, v1
	v_lshl_add_u32 v0, v10, 11, v0
	v_and_b32_e32 v1, 1, v9
	v_lshl_or_b32 v0, v1, 6, v0
	v_lshl_add_u32 v136, v11, 1, v0
	v_mov_b32_e32 v136, v128
	v_lshlrev_b32_e32 v0, 14, v12
	v_and_b32_e32 v0, 0xffff8000, v0
	s_waitcnt vmcnt(6)
	v_lshl_add_u32 v0, v13, 11, v0
	v_and_b32_e32 v1, 1, v12
	s_sext_i32_i8 s1, s20
	s_cselect_b64 s[20:21], -1, 0
	v_lshl_or_b32 v0, v1, 6, v0
	s_add_i32 s65, 0, 0x10000
	s_add_i32 s66, 0, 0x14000
	s_ashr_i32 s63, s94, 31
	s_mov_b32 s64, s94
	v_mov_b32_e32 v137, v131
	v_lshl_add_u32 v138, v14, 1, v0
	v_mov_b32_e32 v138, v132
	v_mov_b32_e32 v139, v131
	v_mov_b64_e32 v[140:141], 0x200
	v_mov_b64_e32 v[142:143], 0x1ff
	v_add_u32_e32 v147, s65, v145
	v_add_u32_e32 v235, s65, v234
	v_add_u32_e32 v148, s66, v145
	v_add_u32_e32 v236, s66, v234
	v_add_u32_e32 v149, 0, v3
	s_mov_b32 s67, 0x40000
	s_mov_b64 s[22:23], 0x48000
	s_mov_b32 s68, 0x48000
	s_mov_b64 s[24:25], 0x50000
	s_mov_b32 s69, 0x50000
	s_mov_b64 s[26:27], 0x58000
	s_mov_b32 s0, 0x58000
	s_barrier
	s_branch .LBB0_922

; __device__ __forceinline__ int fresh_tid() { int t = (int)threadIdx.x; asm volatile("" : "+v"(t)); return t; }
; #define PG8_STAGE(bufoff, gbase, voff) do { _Pragma("unroll") for (int _i = 0; _i < 2; ++_i) \
;         __builtin_amdgcn_global_load_lds((const unsigned*)((const char*)(gbase) + (voff)[_i]), (PG8_LAS unsigned*)(lds + (bufoff) + ldsw + _i * 8192), 16, 0, 0); } while (0)
; #define PG8_WAIT_V(n) asm volatile("s_waitcnt vmcnt(" #n ")" ::: "memory")
; #define PG8_BAR __builtin_amdgcn_s_barrier()
; template <class Epi, class Sched, bool ALIGN_EPI = false, bool SP2 = false>
; __device__ __forceinline__ void gemm_phase(PG8_LAS unsigned char* lds, const Gemm g, const Sched& S, const Epi& E) {
;     const int tid = fresh_tid(), wid = __builtin_amdgcn_readfirstlane(tid >> 6), lane = tid & 63, wr = wid >> 2, wc = wid & 3, fr = lane & 15, fq = lane >> 4;
;     const int K = g.K, nt = K / BK;
;     unsigned voffA[2], voffB[2];
; #pragma unroll
;     for (int i = 0; i < 2; ++i) { int R, C; stage_rc(tid * 16 + i * 8192, R, C); const int Rb = Epi::PERM ? ((R & ~31) + perm32(R & 31)) : R;
;         voffA[i] = (unsigned)(R * K + C) * 2u; voffB[i] = (unsigned)(Rb * K + C) * 2u; }
;     const size_t kstep = (size_t)(BK * 2);
;     const size_t hstep = (size_t)HALF * K * 2;
;     const size_t tstep = 2 * hstep;
;     const unsigned ldsw = (unsigned)wid * 1024u;
;     const int aoff = lds_byte(wr * 64 + fr, fq * 8), boff = lds_byte(wc * 32 + fr, fq * 8);
;     ...
;     if constexpr (SP2) {
;         PG8_STAGE(PG8_SB(0, 0), cB, voffB); PG8_STAGE(PG8_SB(0, 1), cB + hstep, voffB); PG8_STAGE(PG8_SA(0, 0), cA, voffA); PG8_STAGE(PG8_SA(0, 1), cA + hstep, voffA);
;         if (wr == 1) PG8_BAR;
;         PG8_WAIT_V(2); PG8_BAR;
;         PG8_STAGE(PG8_SB(1, 0), cB + kstep, voffB); PG8_STAGE(PG8_SA(1, 0), cA + kstep, voffA); PG8_STAGE(PG8_SB(1, 1), cB + hstep + kstep, voffB);
;         PG8_WAIT_V(6); PG8_BAR;
.LBB0_1112:
	s_waitcnt lgkmcnt(0)
	s_add_u32 s14, s10, 0xb200000
	s_addc_u32 s15, s11, 0
	s_lshl_b32 s0, s16, 5
	s_mov_b64 s[16:17], 0x80
	s_and_b32 s10, s0, 0x60
	s_add_i32 m0, s29, 0x18000
	v_lshl_add_u64 v[6:7], v[6:7], 0, s[16:17]
	s_lshl_b32 s3, s20, 13
	s_lshl_b32 s11, s10, 7
	s_nop 0
	global_load_lds_dwordx4 v[6:7], off
	v_lshl_add_u64 v[4:5], v[4:5], 0, s[16:17]
	s_add_i32 m0, s29, 0x1a000
	s_add_i32 s52, s29, 0x8000
	s_add_i32 s53, s29, 0xa000
	global_load_lds_dwordx4 v[4:5], off
	v_lshl_add_u64 v[0:1], v[0:1], 0, s[16:17]
	s_mov_b32 m0, s52
	s_add_u32 s0, s34, 0x40080
	global_load_lds_dwordx4 v[0:1], off
	v_lshl_add_u64 v[0:1], v[2:3], 0, s[16:17]
	s_mov_b32 m0, s53
	s_addc_u32 s1, s35, 0
	global_load_lds_dwordx4 v[0:1], off
	s_add_i32 m0, s29, 0x1c000
	v_lshl_add_u64 v[0:1], s[0:1], 0, v[132:133]
	global_load_lds_dwordx4 v[0:1], off
	v_lshl_add_u64 v[0:1], s[0:1], 0, v[128:129]
	s_add_i32 m0, s29, 0x1e000
	s_cmpk_lt_u32 s19, 0x100
	global_load_lds_dwordx4 v[0:1], off
	s_waitcnt vmcnt(8)
	s_barrier
	v_lshrrev_b32_e32 v1, 1, v8
	v_and_b32_e32 v1, 24, v1
	v_and_b32_e32 v0, 15, v8
	v_lshlrev_b32_e32 v2, 1, v1
	v_lshl_or_b32 v148, s20, 6, v0
	v_lshl_or_b32 v0, v0, 6, v2
	v_lshlrev_b32_e32 v2, 2, v8
	v_and_b32_e32 v2, 32, v2
	v_bitop3_b32 v3, v0, s3, v2 bitop3:0xde
	v_bitop3_b32 v149, v0, s11, v2 bitop3:0xde
	v_and_b32_e32 v239, 15, v8
	v_and_b32_e32 v240, 7, v239
	v_lshrrev_b32_e32 v239, 3, v239
	v_lshlrev_b32_e32 v239, 10, v239
	v_lshl_add_u32 v239, v240, 7, v239
	v_bfe_u32 v241, v8, 4, 2
	v_xor_b32_e32 v242, v241, v240
	v_or_b32_e32 v241, 4, v241
	v_xor_b32_e32 v243, v241, v240
	v_lshl_add_u32 v242, v242, 4, v239
	v_lshl_add_u32 v243, v243, 4, v239
	v_lshrrev_b32_e32 v244, 8, v8
	v_lshlrev_b32_e32 v244, 13, v244
	v_add_u32_e32 v3, v244, v242
	v_add_u32_e32 v233, v244, v243
	v_bfe_u32 v244, v8, 6, 2
	v_lshlrev_b32_e32 v244, 12, v244
	v_add_u32_e32 v149, v244, v242
	v_add_u32_e32 v234, v244, v243
	v_lshlrev_b32_e32 v0, 14, v13
	v_and_b32_e32 v0, 0xffff8000, v0
	v_or_b32_e32 v150, s10, v1
	v_lshl_add_u32 v0, v12, 11, v0
	v_and_b32_e32 v1, 1, v13
	v_lshl_or_b32 v0, v1, 6, v0
	v_lshl_add_u32 v136, v14, 1, v0
	v_mov_b32_e32 v136, v134
	v_lshlrev_b32_e32 v0, 14, v9
	v_and_b32_e32 v0, 0xffff8000, v0
	s_waitcnt vmcnt(6)
	v_lshl_add_u32 v0, v10, 11, v0
	v_and_b32_e32 v1, 1, v9
	s_sext_i32_i16 s59, s18
	s_cselect_b64 s[18:19], -1, 0
	v_lshl_or_b32 v0, v1, 6, v0
	s_add_i32 s56, 0, 0x10000
	s_add_i32 s57, 0, 0x14000
	s_ashr_i32 s54, s94, 31
	s_mov_b32 s55, s94
	v_mov_b32_e32 v137, v133
	v_lshl_add_u32 v138, v11, 1, v0
	v_mov_b32_e32 v138, v130
	v_mov_b32_e32 v139, v133
	v_mov_b64_e32 v[140:141], 0xb00
	v_mov_b64_e32 v[142:143], 0xaff
	v_add_u32_e32 v151, s56, v149
	v_add_u32_e32 v235, s56, v234
	v_add_u32_e32 v152, s57, v149
	v_add_u32_e32 v236, s57, v234
	v_add_u32_e32 v153, 0, v3
	s_movk_i32 s58, 0x1600
	s_barrier
	s_branch .LBB0_1115

; __device__ __forceinline__ int fresh_tid() { int t = (int)threadIdx.x; asm volatile("" : "+v"(t)); return t; }
; #define PG8_STAGE(bufoff, gbase, voff) do { _Pragma("unroll") for (int _i = 0; _i < 2; ++_i) \
;         __builtin_amdgcn_global_load_lds((const unsigned*)((const char*)(gbase) + (voff)[_i]), (PG8_LAS unsigned*)(lds + (bufoff) + ldsw + _i * 8192), 16, 0, 0); } while (0)
; #define PG8_WAIT_V(n) asm volatile("s_waitcnt vmcnt(" #n ")" ::: "memory")
; #define PG8_BAR __builtin_amdgcn_s_barrier()
; template <class Epi, class Sched, bool ALIGN_EPI = false, bool SP2 = false>
; __device__ __forceinline__ void gemm_phase(PG8_LAS unsigned char* lds, const Gemm g, const Sched& S, const Epi& E) {
;     const int tid = fresh_tid(), wid = __builtin_amdgcn_readfirstlane(tid >> 6), lane = tid & 63, wr = wid >> 2, wc = wid & 3, fr = lane & 15, fq = lane >> 4;
;     const int K = g.K, nt = K / BK;
;     unsigned voffA[2], voffB[2];
; #pragma unroll
;     for (int i = 0; i < 2; ++i) { int R, C; stage_rc(tid * 16 + i * 8192, R, C); const int Rb = Epi::PERM ? ((R & ~31) + perm32(R & 31)) : R;
;         voffA[i] = (unsigned)(R * K + C) * 2u; voffB[i] = (unsigned)(Rb * K + C) * 2u; }
;     const size_t kstep = (size_t)(BK * 2);
;     const size_t hstep = (size_t)HALF * K * 2;
;     const size_t tstep = 2 * hstep;
;     const unsigned ldsw = (unsigned)wid * 1024u;
;     const int aoff = lds_byte(wr * 64 + fr, fq * 8), boff = lds_byte(wc * 32 + fr, fq * 8);
;     ...
;     if constexpr (SP2) {
;         PG8_STAGE(PG8_SB(0, 0), cB, voffB); PG8_STAGE(PG8_SB(0, 1), cB + hstep, voffB); PG8_STAGE(PG8_SA(0, 0), cA, voffA); PG8_STAGE(PG8_SA(0, 1), cA + hstep, voffA);
;         if (wr == 1) PG8_BAR;
;         PG8_WAIT_V(2); PG8_BAR;
;         PG8_STAGE(PG8_SB(1, 0), cB + kstep, voffB); PG8_STAGE(PG8_SA(1, 0), cA + kstep, voffA); PG8_STAGE(PG8_SB(1, 1), cB + hstep + kstep, voffB);
;         PG8_WAIT_V(6); PG8_BAR;
.LBB0_1195:
	s_add_u32 s12, s4, 0x7100000
	s_addc_u32 s13, s5, 0
	s_lshl_b32 s0, s9, 5
	s_mov_b64 s[14:15], 0x80
	s_and_b32 s4, s0, 0x60
	s_add_i32 m0, s47, 0x18000
	v_lshl_add_u64 v[6:7], v[6:7], 0, s[14:15]
	s_lshl_b32 s3, s17, 13
	s_lshl_b32 s5, s4, 7
	s_nop 0
	global_load_lds_dwordx4 v[6:7], off
	v_lshl_add_u64 v[4:5], v[4:5], 0, s[14:15]
	s_add_i32 m0, s47, 0x1a000
	s_add_i32 s52, s47, 0x8000
	s_add_i32 s53, s47, 0xa000
	global_load_lds_dwordx4 v[4:5], off
	v_lshl_add_u64 v[0:1], v[0:1], 0, s[14:15]
	s_mov_b32 m0, s52
	s_add_u32 s0, s30, 0xb0080
	global_load_lds_dwordx4 v[0:1], off
	v_lshl_add_u64 v[0:1], v[2:3], 0, s[14:15]
	s_mov_b32 m0, s53
	s_addc_u32 s1, s31, 0
	global_load_lds_dwordx4 v[0:1], off
	s_add_i32 m0, s47, 0x1c000
	v_lshl_add_u64 v[0:1], s[0:1], 0, v[130:131]
	global_load_lds_dwordx4 v[0:1], off
	v_lshl_add_u64 v[0:1], s[0:1], 0, v[134:135]
	s_add_i32 m0, s47, 0x1e000
	s_mov_b64 s[0:1], 0xb0080
	global_load_lds_dwordx4 v[0:1], off
	s_waitcnt vmcnt(8)
	s_barrier
	v_lshrrev_b32_e32 v1, 1, v8
	v_and_b32_e32 v1, 24, v1
	v_and_b32_e32 v0, 15, v8
	v_lshlrev_b32_e32 v2, 1, v1
	v_lshl_or_b32 v144, s17, 6, v0
	v_lshl_or_b32 v0, v0, 6, v2
	v_lshlrev_b32_e32 v2, 2, v8
	v_and_b32_e32 v2, 32, v2
	v_bitop3_b32 v3, v0, s3, v2 bitop3:0xde
	v_bitop3_b32 v145, v0, s5, v2 bitop3:0xde
	v_and_b32_e32 v239, 15, v8
	v_and_b32_e32 v240, 7, v239
	v_lshrrev_b32_e32 v239, 3, v239
	v_lshlrev_b32_e32 v239, 10, v239
	v_lshl_add_u32 v239, v240, 7, v239
	v_bfe_u32 v241, v8, 4, 2
	v_xor_b32_e32 v242, v241, v240
	v_or_b32_e32 v241, 4, v241
	v_xor_b32_e32 v243, v241, v240
	v_lshl_add_u32 v242, v242, 4, v239
	v_lshl_add_u32 v243, v243, 4, v239
	v_lshrrev_b32_e32 v244, 8, v8
	v_lshlrev_b32_e32 v244, 13, v244
	v_add_u32_e32 v3, v244, v242
	v_add_u32_e32 v233, v244, v243
	v_bfe_u32 v244, v8, 6, 2
	v_lshlrev_b32_e32 v244, 12, v244
	v_add_u32_e32 v145, v244, v242
	v_add_u32_e32 v234, v244, v243
	v_or_b32_e32 v146, s4, v1
	v_lshrrev_b32_e32 v1, 1, v9
	v_mul_lo_u32 v0, v11, s8
	s_mov_b32 s3, 0xb000
	v_mad_u64_u32 v[0:1], s[4:5], v1, s3, v[0:1]
	v_or_b32_e32 v0, v0, v10
	v_add_lshl_u32 v0, v0, v12, 1
	v_mov_b32_e32 v1, v131
	v_lshl_add_u64 v[136:137], v[0:1], 0, s[0:1]
	v_add_u32_e32 v136, 0xb0080, v128
	v_mov_b32_e32 v137, 0
	v_lshrrev_b32_e32 v1, 1, v13
	v_mul_lo_u32 v0, v14, s8
	v_mad_u64_u32 v[0:1], s[4:5], v1, s3, v[0:1]
	s_waitcnt vmcnt(6)
	s_cmpk_lt_u32 s16, 0x100
	v_or_b32_e32 v0, v0, v15
	s_cselect_b64 s[16:17], -1, 0
	v_add_lshl_u32 v0, v0, v16, 1
	v_mov_b32_e32 v1, v131
	s_add_i32 s56, 0, 0x10000
	s_add_i32 s57, 0, 0x14000
	s_sext_i32_i8 s65, s18
	s_ashr_i32 s54, s94, 31
	s_mov_b32 s55, s94
	v_lshl_add_u64 v[138:139], v[0:1], 0, s[0:1]
	v_add_u32_e32 v138, 0xb0080, v132
	v_mov_b32_e32 v139, 0
	v_mov_b64_e32 v[140:141], 0x200
	v_mov_b64_e32 v[142:143], 0x1ff
	v_add_u32_e32 v147, s56, v145
	v_add_u32_e32 v235, s56, v234
	v_add_u32_e32 v148, s57, v145
	v_add_u32_e32 v236, s57, v234
	v_add_u32_e32 v149, 0, v3
	s_mov_b64 s[18:19], 0x40000
	s_mov_b32 s58, 0x40000
	s_mov_b64 s[20:21], 0x48000
	s_mov_b32 s59, 0x48000
	s_mov_b64 s[22:23], 0x50000
	s_mov_b32 s60, 0x50000
	s_mov_b64 s[24:25], 0x58000
	s_mov_b32 s61, 0x58000
	s_barrier
	s_branch .LBB0_1198
